# NSA item prologue: compressed K/V tile loads issued together with the q/gate loads before the first barrier; nsa_cnt exchange through ds_write/ds_read instead of flat LDS accesses
# baseline (speedup 1.0000x reference)
; DEVI float bf2f(bfu h) { return __uint_as_float(((unsigned)h) << 16); }
; DEVI float sigmoidf_(float x) { return __builtin_amdgcn_rcpf(1.f + __expf(-x)); }
; DEVI void nsa_item(const Params& p, int l, int item, char* lds_raw, volatile int* nsa_cnt) {
;     ...
;   bf16x8 qf[2][2];
; #pragma unroll
;   for (int g = 0; g < 2; ++g)
; #pragma unroll
;     for (int ks = 0; ks < 2; ++ks) qf[g][ks] = *(const bf16x8*)(myrow + C_Q + (h * 2 + g) * 64 + ks * 32 + fq * 8);
;   float gate[2][3];
; #pragma unroll
;   for (int g = 0; g < 2; ++g)
; #pragma unroll
;     for (int br = 0; br < 3; ++br) gate[g][br] = sigmoidf_(bf2f(myrow[C_NG + (h * 2 + g) * 3 + br]));
;   f32x4 fin[2][4];
; #pragma unroll
;   for (int g = 0; g < 2; ++g)
; #pragma unroll
;     for (int d = 0; d < 4; ++d) fin[g][d] = f32x4{0.f, 0.f, 0.f, 0.f};
;   const int ntile = (t0 + 32 >= 1024) ? 2 : 1;
;   __syncthreads();
;   {
;     const bfu* kc = (const bfu*)(p.ws + OFF_KCMP) + (long)(b * 2 + h) * 128 * 64;
;     const bfu* vc = (const bfu*)(p.ws + OFF_VCT) + (long)(b * 2 + h) * 64 * 128;
;     for (int i = 0; i < 2 * ntile; ++i) {
;       int id = tid + 256 * i;
;       int row = id >> 3, ch = id & 7;
;       *(uint4*)(Kb + row * LS + ch * 8) = *(const uint4*)(kc + row * 64 + ch * 8);
;     }
;     for (int i = 0; i < 2 * ntile; ++i) {
;       int id = tid + 256 * i;
;       int tt = id >> 9, d = (id >> 3) & 63, ch = id & 7;
;       *(uint4*)(Vb + tt * 64 * LS + d * LS + ch * 8) = *(const uint4*)(vc + d * 128 + tt * 64 + ch * 8);
;     }
;   }
.LBB0_481:
	s_ashr_i32 s28, s27, 4
	v_mov_b32_e32 v83, v221
	s_sub_i32 s25, 31, s28
	s_lshl_b32 s4, s25, 6
	v_ashrrev_i32_e32 v0, 2, v83
	v_bfi_b32 v177, -16, v0, v83
	s_bfe_u32 s20, s27, 0x30001
	v_add_u32_e32 v84, s4, v177
	s_lshl_b32 s30, s20, 11
	v_ashrrev_i32_e32 v85, 31, v84
	v_readlane_b32 s0, v243, 0
	v_lshl_add_u64 v[184:185], s[30:31], 0, v[84:85]
	s_waitcnt lgkmcnt(0)
	v_mov_b64_e32 v[2:3], s[6:7]
	v_bfe_u32 v82, v83, 4, 2
	v_mad_u64_u32 v[18:19], s[0:1], v184, s72, v[2:3]
	s_and_b32 s23, s27, 1
	v_mad_i32_i24 v19, v185, s72, v19
	v_lshlrev_b32_e32 v0, 4, v82
	v_lshl_add_u64 v[2:3], v[18:19], 0, v[0:1]
	s_lshl_b32 s30, s23, 8
	v_lshl_add_u64 v[14:15], v[2:3], 0, s[30:31]
	s_mul_i32 s30, s23, 12
	v_lshl_add_u64 v[18:19], v[18:19], 0, s[30:31]
	s_movk_i32 s0, 0x1000
	global_load_dwordx4 v[2:5], v[14:15], off offset:1024
	global_load_dwordx4 v[6:9], v[14:15], off offset:1088
	global_load_dwordx4 v[10:13], v[14:15], off offset:1152
	s_nop 0
	global_load_dwordx4 v[14:17], v[14:15], off offset:1216
	v_add_co_u32_e32 v18, vcc, s0, v18
	s_lshl_b32 s0, s27, 14
	s_nop 0
	v_addc_co_u32_e32 v19, vcc, 0, v19, vcc
	global_load_dwordx3 v[174:176], v[18:19], off offset:1536
	s_mov_b32 s13, s22
	s_mov_b32 s22, s33
	s_mov_b32 s33, s19
	s_mov_b32 s29, s18
	s_lshl_b32 s11, s23, 7
	s_and_b32 s0, s0, 0x3c000
	v_readlane_b32 s18, v243, 14
	v_readlane_b32 s19, v243, 15
	s_add_u32 s38, s18, s0
	s_addc_u32 s39, s19, 0
	s_cmpk_gt_u32 s4, 0x3df
	s_cselect_b64 s[36:37], -1, 0
	v_lshlrev_b32_e32 v0, 3, v83
	s_and_b64 s[4:5], s[36:37], exec
	v_and_b32_e32 v18, 56, v0
	s_cselect_b32 s4, 4, 2
	v_lshlrev_b32_e32 v0, 1, v18
	v_and_b32_e32 v153, 15, v83
	v_lshlrev_b32_e32 v93, 3, v82
	v_lshl_add_u64 v[20:21], s[38:39], 0, v[0:1]
	v_add_u32_e32 v0, s26, v0
	s_mov_b32 s1, s4
	v_mov_b32_e32 v19, v83
	s_movk_i32 s5, 0x90
	v_ashrrev_i32_e32 v26, 3, v83
	v_lshlrev_b32_e32 v22, 7, v26
	v_mov_b32_e32 v23, 0
	s_mov_b64 s[38:39], 0x1000
	v_lshl_add_u64 v[22:23], v[20:21], 0, v[22:23]
	v_mad_u32_u24 v26, v26, s5, v0
	global_load_dwordx4 v[246:249], v[22:23], off
	v_lshl_add_u64 v[22:23], v[22:23], 0, s[38:39]
	global_load_dwordx4 v[250:253], v[22:23], off
	s_cmp_eq_u32 s4, 4
	s_cbranch_scc0 .Lcmp_l2
	v_lshl_add_u64 v[22:23], v[22:23], 0, s[38:39]
	global_load_dwordx4 v[234:237], v[22:23], off
	v_lshl_add_u64 v[22:23], v[22:23], 0, s[38:39]
	global_load_dwordx4 v[238:241], v[22:23], off
.Lcmp_l2:
	v_readlane_b32 s1, v243, 16
	s_add_u32 s0, s1, s0
	v_readlane_b32 s1, v243, 17
	s_mov_b64 s[18:19], s[6:7]
	s_addc_u32 s1, s1, 0
	v_ashrrev_i32_e32 v24, 3, v83
	v_lshlrev_b32_e32 v0, 1, v18
	v_lshl_add_u32 v20, v24, 8, v0
	v_mov_b32_e32 v21, 0
	s_mov_b64 s[38:39], 0x2000
	v_lshl_add_u64 v[20:21], s[0:1], 0, v[20:21]
	v_mul_u32_u24_e32 v24, 0x90, v24
	v_add3_u32 v24, v24, v0, s26
	global_load_dwordx4 v[104:107], v[20:21], off
	v_lshl_add_u64 v[22:23], v[20:21], 0, s[38:39]
	global_load_dwordx4 v[108:111], v[22:23], off
	s_cmp_eq_u32 s4, 4
	s_cbranch_scc0 .Lcmp_l3
	global_load_dwordx4 v[112:115], v[20:21], off offset:128
	global_load_dwordx4 v[116:119], v[22:23], off offset:128
.Lcmp_l3:
	s_waitcnt vmcnt(0)
	s_barrier
	ds_write_b128 v26, v[246:249]
	ds_write_b128 v26, v[250:253] offset:4608
	ds_write_b128 v24, v[104:107] offset:18432
	ds_write_b128 v24, v[108:111] offset:23040
	s_cmp_eq_u32 s4, 4
	s_cbranch_scc0 .Lcmp_done
	ds_write_b128 v26, v[234:237] offset:9216
	ds_write_b128 v26, v[238:241] offset:13824
	ds_write_b128 v24, v[112:115] offset:27648
	ds_write_b128 v24, v[116:119] offset:32256

; DEVI int vhalf() { int t = threadIdx.x >> 8; t = __builtin_amdgcn_readfirstlane(t); return t; }
; DEVI void nsa_item(const Params& p, int l, int item, char* lds_raw, volatile int* nsa_cnt) {
;     ...
;   __syncthreads();
;   const unsigned mysel = selm[tokl];
;   const unsigned ormask = selm[64];
;   uint4 rk0, rk1, rv0, rv1;
;     ...
;   int kvo = 0;
;   {
;     AttnState st;
;     attn_init(st);
;     const bfu* kbase = proj + tokbase * LDP + C_KS + h * 64;
;     const bfu* vbase = (const bfu*)(p.ws + OFF_VST) + ((long)b * 128 + h * 64) * SEQ;
;     unsigned rem = ormask & ((2u << qt) - 1u);
;     if (tid == 0) nsa_cnt[vhalf()] = __popc(rem);
;     __syncthreads();
;     const int niter = max(nsa_cnt[0], nsa_cnt[1]);
;     int j = __ffs(rem) - 1;
;     KV_LOAD(kbase, vbase, j);
.LBB0_498:
	s_or_b64 exec, exec, s[4:5]
	v_mov_b32_e32 v50, s26
	s_waitcnt lgkmcnt(0)
	s_barrier
	ds_read_b32 v50, v50 offset:62464
	v_lshl_add_u32 v51, v177, 2, s26
	ds_read_b32 v157, v51 offset:62208
	s_lshl_b32 s0, 2, s25
	s_add_i32 s0, s0, -1
	s_waitcnt lgkmcnt(1)
	v_readfirstlane_b32 s1, v50
	v_lshlrev_b32_e32 v203, 2, v82
	s_and_b32 s4, s1, s0
	v_cmp_eq_u32_e32 vcc, 0, v83
	s_and_saveexec_b64 s[0:1], vcc
	s_cbranch_execz .LBB0_500
	v_readfirstlane_b32 s30, v220
	s_lshr_b32 s30, s30, 6
	s_and_b32 s30, s30, 0x3fffffc
	s_mov_b64 s[36:37], src_shared_base
	s_bcnt1_i32_b32 s5, s4
	s_addk_i32 s30, 0xc10
	v_mov_b32_e32 v50, s30
	v_mov_b32_e32 v52, s5
	ds_write_b32 v50, v52
.LBB0_500:
	s_or_b64 exec, exec, s[0:1]
	s_mov_b64 s[0:1], src_shared_base
	v_mov_b32_e32 v179, s1
	v_mov_b32_e32 v181, s1
	s_waitcnt lgkmcnt(0)
	s_barrier
	ds_read_b32 v82, v178
	ds_read_b32 v84, v180
	s_mul_i32 s0, s20, 0xc00000
	v_ashrrev_i32_e32 v186, 3, v83
	s_add_u32 s0, s6, s0
	v_add_u32_e32 v142, 32, v186
	s_addc_u32 s1, s7, 0
	v_mov_b32_e32 v66, v1
	v_mov_b32_e32 v67, v1
	v_mov_b32_e32 v68, v1
	v_mov_b32_e32 v69, v1
	v_ashrrev_i32_e32 v143, 31, v142
	s_add_u32 s36, s0, s11
	v_ashrrev_i32_e32 v187, 31, v186
	v_mov_b64_e32 v[62:63], v[66:67]
	v_mov_b64_e32 v[58:59], v[66:67]
	v_mov_b64_e32 v[50:51], v[66:67]
	v_mov_b64_e32 v[80:81], v[68:69]
	v_mov_b64_e32 v[76:77], v[68:69]
	v_mov_b64_e32 v[72:73], v[68:69]
	v_mov_b64_e32 v[54:55], v[66:67]
	v_mov_b64_e32 v[104:105], v[68:69]
	v_lshlrev_b64 v[146:147], 11, v[142:143]
	s_addc_u32 s37, s1, 0
	s_lshl_b32 s0, s20, 18
	s_lshl_b32 s1, s23, 17
	v_mov_b64_e32 v[108:109], v[68:69]
	v_mov_b32_e32 v179, 0
	v_mov_b64_e32 v[64:65], v[68:69]
	v_mov_b64_e32 v[60:61], v[68:69]
	v_mov_b64_e32 v[52:53], v[68:69]
	v_mov_b64_e32 v[78:79], v[66:67]
	v_mov_b64_e32 v[74:75], v[66:67]
	v_mov_b64_e32 v[70:71], v[66:67]
	v_mov_b64_e32 v[56:57], v[68:69]
	v_mov_b64_e32 v[102:103], v[66:67]
	v_lshlrev_b64 v[144:145], 11, v[186:187]
	s_or_b32 s20, s0, s1
	v_lshl_add_u64 v[188:189], s[36:37], 0, v[0:1]
	v_mov_b64_e32 v[106:107], v[66:67]
	s_waitcnt lgkmcnt(0)
	v_max_i32_e32 v143, v82, v84
	v_cmp_lt_i32_e32 vcc, 0, v143
	s_and_saveexec_b64 s[64:65], vcc
	s_cbranch_execz .LBB0_517
	s_lshl_b32 s0, s20, 1
	v_readlane_b32 s1, v243, 18
	s_add_u32 s0, s1, s0
	v_readlane_b32 s1, v243, 19
	s_addc_u32 s1, s1, 0
	v_cmp_eq_u32_e32 vcc, 0, v153
	v_lshl_add_u64 v[50:51], v[144:145], 1, s[0:1]
	v_lshl_add_u64 v[52:53], v[146:147], 1, s[0:1]
	s_ff1_i32_b32 s0, s4
	s_lshl_b32 s0, s0, 6
	s_cmp_lg_u32 s4, 0
	s_cselect_b32 s0, s0, 0xffffffc0
	s_ashr_i32 s1, s0, 31
	s_lshl_b64 s[38:39], s[0:1], 1
	v_lshl_add_u64 v[54:55], v[52:53], 0, s[38:39]
	v_lshl_add_u64 v[56:57], v[50:51], 0, s[38:39]
	v_lshl_add_u64 v[54:55], v[54:55], 0, v[0:1]
	v_lshl_add_u64 v[56:57], v[56:57], 0, v[0:1]
	global_load_dwordx4 v[86:89], v[54:55], off
	global_load_dwordx4 v[90:93], v[56:57], off
	v_add_u32_e32 v56, s0, v142
	v_mov_b64_e32 v[54:55], s[36:37]
	v_mad_i64_i32 v[56:57], s[38:39], v56, s72, v[54:55]
	v_add_u32_e32 v58, s0, v186
	v_lshl_add_u64 v[56:57], v[56:57], 0, v[0:1]
	v_mad_i64_i32 v[54:55], s[0:1], v58, s72, v[54:55]
	v_lshl_add_u64 v[54:55], v[54:55], 0, v[0:1]
	global_load_dwordx4 v[94:97], v[56:57], off offset:2048
	global_load_dwordx4 v[98:101], v[54:55], off offset:2048
	v_lshl_add_u64 v[148:149], v[50:51], 0, v[0:1]
	v_cndmask_b32_e32 v50, 0, v228, vcc
	s_movk_i32 s0, 0x90
	v_perm_b32 v82, v50, v50, s16
	v_mul_lo_u32 v50, v186, s0
	v_mov_b32_e32 v106, v1
	v_mov_b32_e32 v107, v1
	v_lshl_add_u64 v[150:151], v[52:53], 0, v[0:1]
	v_add_u32_e32 v158, s26, v50
	v_mov_b32_e32 v108, v1
	v_mov_b32_e32 v109, v1
	v_mov_b64_e32 v[102:103], v[106:107]
	v_mov_b64_e32 v[54:55], v[106:107]
	v_mov_b64_e32 v[70:71], v[106:107]
	v_mov_b64_e32 v[74:75], v[106:107]
	v_mov_b64_e32 v[78:79], v[106:107]
	v_mov_b64_e32 v[50:51], v[106:107]
	v_mov_b64_e32 v[58:59], v[106:107]
	v_mov_b64_e32 v[62:63], v[106:107]
	v_mov_b64_e32 v[66:67], v[106:107]
	s_mov_b32 s23, 0
	v_mov_b32_e32 v83, v82
	v_mov_b32_e32 v84, v82
	v_mov_b32_e32 v85, v82
	v_mov_b32_e32 v152, 0xf149f2ca
	s_mov_b64 s[66:67], 0
	v_mov_b64_e32 v[104:105], v[108:109]
	v_mov_b64_e32 v[56:57], v[108:109]
	v_mov_b64_e32 v[72:73], v[108:109]
	v_mov_b64_e32 v[76:77], v[108:109]
	v_mov_b64_e32 v[80:81], v[108:109]
	v_mov_b64_e32 v[52:53], v[108:109]
	v_mov_b64_e32 v[60:61], v[108:109]
	v_mov_b64_e32 v[64:65], v[108:109]
	v_mov_b64_e32 v[68:69], v[108:109]
	v_mov_b32_e32 v154, 0xf149f2ca
	v_readfirstlane_b32 s30, v220
	s_lshr_b32 s30, s30, 8
	s_cmp_lg_u32 s30, 1
	s_cbranch_scc1 .Lsel_skew_in
	s_barrier
